# P10 MIXB/MB loads default policy instead of nt, on top of v109
# baseline (speedup 1.0000x reference)
.LBB0_1035:
	s_ashr_i32 s5, s4, 31
	s_lshl_b64 s[0:1], s[4:5], 6
	s_waitcnt vmcnt(12)
	v_lshl_add_u64 v[32:33], v[52:53], 0, s[0:1]
	s_waitcnt lgkmcnt(0)
	global_load_dwordx4 v[88:91], v[32:33], off
	v_lshl_add_u64 v[32:33], v[54:55], 0, s[0:1]
	global_load_dwordx4 v[92:95], v[32:33], off
	s_add_i32 s6, s12, s4
	s_cmp_lt_i32 s6, 0x8000
	s_cselect_b32 s0, s6, s4
	s_ashr_i32 s1, s0, 31
	s_lshl_b64 s[2:3], s[0:1], 6
	v_lshl_add_u64 v[32:33], v[52:53], 0, s[2:3]
	global_load_dwordx4 v[96:99], v[32:33], off
	v_lshl_add_u64 v[32:33], v[54:55], 0, s[2:3]
	global_load_dwordx4 v[100:103], v[32:33], off
	s_lshl_b64 s[8:9], s[4:5], 12
	s_lshl_b64 s[2:3], s[4:5], 11
	v_lshl_add_u64 v[36:37], v[56:57], 0, s[8:9]
	v_lshl_add_u64 v[32:33], v[60:61], 0, s[2:3]
	v_lshl_add_u64 v[34:35], v[58:59], 0, s[2:3]
	global_load_dwordx4 v[48:51], v[36:37], off offset:3072 nt
	global_load_dwordx4 v[104:107], v[36:37], off offset:2048 nt
	global_load_dwordx2 v[80:81], v[32:33], off offset:1536
	global_load_dwordx2 v[116:117], v[32:33], off offset:1024
	global_load_dwordx2 v[118:119], v[32:33], off offset:512
	global_load_dwordx2 v[120:121], v[32:33], off
	global_load_dwordx2 v[82:83], v[34:35], off offset:1536
	global_load_dwordx2 v[122:123], v[34:35], off offset:1024
	global_load_dwordx2 v[124:125], v[34:35], off offset:512
	global_load_dwordx2 v[126:127], v[34:35], off
	global_load_dwordx4 v[108:111], v[36:37], off offset:1024 nt
	global_load_dwordx4 v[112:115], v[36:37], off nt
	s_lshl_b64 s[2:3], s[0:1], 12
	s_lshl_b64 s[0:1], s[0:1], 11
	s_waitcnt vmcnt(20)
	v_lshl_add_u64 v[64:65], v[56:57], 0, s[2:3]
	v_lshl_add_u64 v[68:69], v[58:59], 0, s[0:1]
	v_lshl_add_u64 v[128:129], v[60:61], 0, s[0:1]
	global_load_dwordx4 v[44:47], v[64:65], off nt
	global_load_dwordx4 v[40:43], v[64:65], off offset:1024 nt
	global_load_dwordx4 v[36:39], v[64:65], off offset:2048 nt
	global_load_dwordx4 v[32:35], v[64:65], off offset:3072 nt
	global_load_dwordx2 v[78:79], v[68:69], off
	global_load_dwordx2 v[74:75], v[68:69], off offset:512
	global_load_dwordx2 v[70:71], v[68:69], off offset:1024
	global_load_dwordx2 v[66:67], v[68:69], off offset:1536
	global_load_dwordx2 v[76:77], v[128:129], off
	global_load_dwordx2 v[72:73], v[128:129], off offset:512
	s_nop 0
	global_load_dwordx2 v[68:69], v[128:129], off offset:1024
	global_load_dwordx2 v[64:65], v[128:129], off offset:1536
	s_cmpk_gt_i32 s6, 0x7fff
	s_waitcnt vmcnt(27)
	v_mov_b32_e32 v128, v89
	v_mov_b32_e32 v129, v90
	v_mov_b32_e32 v89, v91
	s_waitcnt vmcnt(26)
	v_mov_b32_e32 v90, v93
	v_mov_b32_e32 v91, v94
	v_mov_b32_e32 v93, v95
	v_pk_add_f32 v[88:89], v[128:129], v[88:89]
	v_pk_add_f32 v[90:91], v[90:91], v[92:93]
	v_add_f32_e32 v88, v88, v89
	v_add_f32_e32 v89, v90, v91
	ds_bpermute_b32 v91, v84, v89
	ds_bpermute_b32 v90, v84, v88
	s_waitcnt vmcnt(25)
	v_add_f32_e32 v92, v96, v97
	v_add_f32_e32 v93, v98, v99
	s_waitcnt vmcnt(24)
	v_add_f32_e32 v94, v100, v101
	s_waitcnt lgkmcnt(1)
	v_add_f32_e32 v91, v89, v91
	v_add_f32_e32 v95, v102, v103
	v_add_f32_e32 v92, v92, v93
	s_waitcnt lgkmcnt(0)
	v_add_f32_e32 v96, v88, v90
	ds_bpermute_b32 v97, v85, v91
	v_add_f32_e32 v93, v94, v95
	ds_bpermute_b32 v94, v84, v92
	ds_bpermute_b32 v98, v85, v96
	ds_bpermute_b32 v95, v84, v93
	s_waitcnt lgkmcnt(3)
	v_add_f32_e32 v91, v91, v97
	v_fmamk_f32 v91, v91, 0x3a800000, v86
	s_waitcnt lgkmcnt(2)
	v_add_f32_e32 v88, v92, v94
	s_waitcnt lgkmcnt(1)
	v_add_f32_e32 v92, v96, v98
	s_waitcnt lgkmcnt(0)
	v_add_f32_e32 v90, v93, v95
	v_fmamk_f32 v92, v92, 0x3a800000, v86
	v_mul_f32_e32 v93, 0x4f800000, v91
	v_cmp_gt_f32_e32 vcc, s11, v91
	v_mul_f32_e32 v94, 0x4f800000, v92
	v_cmp_gt_f32_e64 s[0:1], s11, v92
	v_cndmask_b32_e32 v93, v91, v93, vcc
	v_sqrt_f32_e32 v95, v93
	v_cndmask_b32_e64 v92, v92, v94, s[0:1]
	v_sqrt_f32_e32 v94, v92
	ds_bpermute_b32 v89, v85, v88
	v_add_u32_e32 v96, -1, v95
	v_fma_f32 v100, -v96, v95, v93
	v_add_u32_e32 v98, -1, v94
	v_add_u32_e32 v97, 1, v95
	v_fma_f32 v102, -v98, v94, v92
	v_cmp_ge_f32_e64 s[2:3], 0, v100
	v_add_u32_e32 v99, 1, v94
	v_fma_f32 v101, -v97, v95, v93
	v_cndmask_b32_e64 v95, v95, v96, s[2:3]
	v_cmp_ge_f32_e64 s[2:3], 0, v102
	v_fma_f32 v103, -v99, v94, v92
	s_waitcnt vmcnt(18)
	v_lshlrev_b32_e32 v102, 16, v121
	v_cndmask_b32_e64 v94, v94, v98, s[2:3]
	v_cmp_lt_f32_e64 s[2:3], 0, v101
	v_lshl_add_u64 v[100:101], v[62:63], 0, s[8:9]
	ds_bpermute_b32 v91, v85, v90
	v_cndmask_b32_e64 v95, v95, v97, s[2:3]
	v_mul_f32_e32 v96, 0x37800000, v95
	v_cndmask_b32_e32 v95, v95, v96, vcc
	v_cmp_class_f32_e32 vcc, v93, v87
	v_cmp_lt_f32_e64 s[2:3], 0, v103
	v_and_b32_e32 v103, 0xffff0000, v121
	v_cndmask_b32_e32 v93, v95, v93, vcc
	v_cndmask_b32_e64 v94, v94, v99, s[2:3]
	v_div_scale_f32 v95, s[2:3], v93, v93, 1.0
	v_rcp_f32_e32 v96, v95
	v_mul_f32_e32 v97, 0x37800000, v94
	v_cndmask_b32_e64 v94, v94, v97, s[0:1]
	v_div_scale_f32 v97, vcc, 1.0, v93, 1.0
	v_fma_f32 v98, -v95, v96, 1.0
	v_fmac_f32_e32 v96, v98, v96
	v_mul_f32_e32 v98, v97, v96
	v_cmp_class_f32_e64 s[0:1], v92, v87
	v_fma_f32 v99, -v95, v98, v97
	v_fmac_f32_e32 v98, v99, v96
	v_cndmask_b32_e64 v92, v94, v92, s[0:1]
	v_div_scale_f32 v94, s[0:1], v92, v92, 1.0
	v_fma_f32 v95, -v95, v98, v97
	v_rcp_f32_e32 v97, v94
	v_div_fmas_f32 v95, v95, v96, v98
	v_div_fixup_f32 v96, v95, v93, 1.0
	v_fma_f32 v93, -v94, v97, 1.0
	v_fmac_f32_e32 v97, v93, v97
	v_div_scale_f32 v93, vcc, 1.0, v92, 1.0
	v_mul_f32_e32 v95, v93, v97
	v_fma_f32 v98, -v94, v95, v93
	v_fmac_f32_e32 v95, v98, v97
	v_fma_f32 v93, -v94, v95, v93
	v_div_fmas_f32 v93, v93, v97, v95
	v_div_fixup_f32 v98, v93, v92, 1.0
	s_waitcnt vmcnt(14)
	v_lshlrev_b32_e32 v92, 16, v126
	v_and_b32_e32 v93, 0xffff0000, v126
	v_pk_mul_f32 v[92:93], v[98:99], v[92:93] op_sel_hi:[0,1]
	v_lshlrev_b32_e32 v94, 16, v120
	v_and_b32_e32 v95, 0xffff0000, v120
	s_waitcnt vmcnt(12)
	v_pk_fma_f32 v[92:93], v[28:29], v[92:93], v[112:113]
	v_pk_mul_f32 v[94:95], v[96:97], v[94:95] op_sel_hi:[0,1]
	v_pk_fma_f32 v[92:93], v[20:21], v[94:95], v[92:93]
	v_lshlrev_b32_e32 v94, 16, v127
	v_and_b32_e32 v95, 0xffff0000, v127
	v_pk_mul_f32 v[94:95], v[98:99], v[94:95] op_sel_hi:[0,1]
	v_pk_fma_f32 v[94:95], v[30:31], v[94:95], v[114:115]
	v_pk_mul_f32 v[102:103], v[96:97], v[102:103] op_sel_hi:[0,1]
	v_pk_fma_f32 v[94:95], v[22:23], v[102:103], v[94:95]
	global_store_dwordx4 v[100:101], v[92:95], off nt
	v_lshlrev_b32_e32 v102, 16, v119
	v_and_b32_e32 v103, 0xffff0000, v119
	v_lshlrev_b32_e32 v92, 16, v124
	v_and_b32_e32 v93, 0xffff0000, v124
	v_pk_mul_f32 v[92:93], v[98:99], v[92:93] op_sel_hi:[0,1]
	v_lshlrev_b32_e32 v94, 16, v118
	v_and_b32_e32 v95, 0xffff0000, v118
	v_pk_fma_f32 v[92:93], v[24:25], v[92:93], v[108:109]
	v_pk_mul_f32 v[94:95], v[96:97], v[94:95] op_sel_hi:[0,1]
	v_pk_fma_f32 v[92:93], v[16:17], v[94:95], v[92:93]
	v_lshlrev_b32_e32 v94, 16, v125
	v_and_b32_e32 v95, 0xffff0000, v125
	v_pk_mul_f32 v[94:95], v[98:99], v[94:95] op_sel_hi:[0,1]
	v_pk_fma_f32 v[94:95], v[26:27], v[94:95], v[110:111]
	v_pk_mul_f32 v[102:103], v[96:97], v[102:103] op_sel_hi:[0,1]
	v_pk_fma_f32 v[94:95], v[18:19], v[102:103], v[94:95]
	global_store_dwordx4 v[100:101], v[92:95], off offset:1024 nt
	v_lshlrev_b32_e32 v102, 16, v117
	v_and_b32_e32 v103, 0xffff0000, v117
	v_lshlrev_b32_e32 v92, 16, v122
	v_and_b32_e32 v93, 0xffff0000, v122
	v_pk_mul_f32 v[92:93], v[98:99], v[92:93] op_sel_hi:[0,1]
	v_lshlrev_b32_e32 v94, 16, v116
	v_and_b32_e32 v95, 0xffff0000, v116
	v_pk_fma_f32 v[92:93], v[12:13], v[92:93], v[104:105]
	v_pk_mul_f32 v[94:95], v[96:97], v[94:95] op_sel_hi:[0,1]
	v_pk_fma_f32 v[92:93], v[4:5], v[94:95], v[92:93]
	v_lshlrev_b32_e32 v94, 16, v123
	v_and_b32_e32 v95, 0xffff0000, v123
	v_pk_mul_f32 v[94:95], v[98:99], v[94:95] op_sel_hi:[0,1]
	v_pk_fma_f32 v[94:95], v[14:15], v[94:95], v[106:107]
	v_pk_mul_f32 v[102:103], v[96:97], v[102:103] op_sel_hi:[0,1]
	v_pk_fma_f32 v[94:95], v[6:7], v[102:103], v[94:95]
	global_store_dwordx4 v[100:101], v[92:95], off offset:2048 nt
	s_nop 1
	v_lshlrev_b32_e32 v92, 16, v82
	v_and_b32_e32 v93, 0xffff0000, v82
	v_pk_mul_f32 v[92:93], v[98:99], v[92:93] op_sel_hi:[0,1]
	v_lshlrev_b32_e32 v82, 16, v83
	v_and_b32_e32 v83, 0xffff0000, v83
	v_pk_fma_f32 v[48:49], v[8:9], v[92:93], v[48:49]
	v_lshlrev_b32_e32 v92, 16, v80
	v_and_b32_e32 v93, 0xffff0000, v80
	v_pk_mul_f32 v[82:83], v[98:99], v[82:83] op_sel_hi:[0,1]
	v_lshlrev_b32_e32 v80, 16, v81
	v_and_b32_e32 v81, 0xffff0000, v81
	v_pk_mul_f32 v[92:93], v[96:97], v[92:93] op_sel_hi:[0,1]
	v_pk_fma_f32 v[50:51], v[10:11], v[82:83], v[50:51]
	v_pk_mul_f32 v[80:81], v[96:97], v[80:81] op_sel_hi:[0,1]
	v_pk_fma_f32 v[48:49], v[0:1], v[92:93], v[48:49]
	v_pk_fma_f32 v[50:51], v[2:3], v[80:81], v[50:51]
	global_store_dwordx4 v[100:101], v[48:51], off offset:3072 nt
	s_cbranch_scc1 .LBB0_1034
	s_waitcnt lgkmcnt(0)
	v_add_f32_e32 v48, v90, v91
	v_fmamk_f32 v48, v48, 0x3a800000, v86
	v_mul_f32_e32 v49, 0x4f800000, v48
	v_cmp_gt_f32_e32 vcc, s11, v48
	v_add_f32_e32 v81, v88, v89
	v_fmamk_f32 v81, v81, 0x3a800000, v86
	v_cndmask_b32_e32 v48, v48, v49, vcc
	v_sqrt_f32_e32 v49, v48
	v_mul_f32_e32 v82, 0x4f800000, v81
	s_ashr_i32 s7, s6, 31
	v_add_u32_e32 v50, -1, v49
	v_fma_f32 v80, -v50, v49, v48
	v_add_u32_e32 v51, 1, v49
	v_cmp_ge_f32_e64 s[0:1], 0, v80
	s_nop 1
	v_cndmask_b32_e64 v50, v49, v50, s[0:1]
	v_fma_f32 v49, -v51, v49, v48
	v_cmp_lt_f32_e64 s[0:1], 0, v49
	s_nop 1
	v_cndmask_b32_e64 v49, v50, v51, s[0:1]
	v_mul_f32_e32 v50, 0x37800000, v49
	v_cndmask_b32_e32 v49, v49, v50, vcc
	v_cmp_class_f32_e32 vcc, v48, v87
	s_nop 1
	v_cndmask_b32_e32 v48, v49, v48, vcc
	v_div_scale_f32 v49, s[0:1], v48, v48, 1.0
	v_rcp_f32_e32 v50, v49
	v_cmp_gt_f32_e64 s[0:1], s11, v81
	v_fma_f32 v51, -v49, v50, 1.0
	s_nop 0
	v_cndmask_b32_e64 v81, v81, v82, s[0:1]
	v_fmac_f32_e32 v50, v51, v50
	v_div_scale_f32 v51, vcc, 1.0, v48, 1.0
	v_sqrt_f32_e32 v82, v81
	v_mul_f32_e32 v80, v51, v50
	v_fma_f32 v83, -v49, v80, v51
	v_fmac_f32_e32 v80, v83, v50
	v_fma_f32 v49, -v49, v80, v51
	v_add_u32_e32 v51, -1, v82
	v_fma_f32 v83, -v51, v82, v81
	v_cmp_ge_f32_e64 s[2:3], 0, v83
	v_add_u32_e32 v83, 1, v82
	v_div_fmas_f32 v49, v49, v50, v80
	v_cndmask_b32_e64 v51, v82, v51, s[2:3]
	v_fma_f32 v82, -v83, v82, v81
	v_cmp_lt_f32_e64 s[2:3], 0, v82
	v_div_fixup_f32 v48, v49, v48, 1.0
	s_nop 0
	v_cndmask_b32_e64 v51, v51, v83, s[2:3]
	v_mul_f32_e32 v82, 0x37800000, v51
	v_cndmask_b32_e64 v51, v51, v82, s[0:1]
	v_cmp_class_f32_e64 s[0:1], v81, v87
	s_waitcnt vmcnt(11)
	v_and_b32_e32 v83, 0xffff0000, v78
	v_cndmask_b32_e64 v51, v51, v81, s[0:1]
	v_div_scale_f32 v81, s[0:1], v51, v51, 1.0
	v_rcp_f32_e32 v82, v81
	s_lshl_b64 s[0:1], s[6:7], 12
	v_fma_f32 v49, -v81, v82, 1.0
	v_fmac_f32_e32 v82, v49, v82
	v_div_scale_f32 v49, vcc, 1.0, v51, 1.0
	v_mul_f32_e32 v50, v49, v82
	v_fma_f32 v80, -v81, v50, v49
	v_fmac_f32_e32 v50, v80, v82
	v_fma_f32 v49, -v81, v50, v49
	v_div_fmas_f32 v49, v49, v82, v50
	v_div_fixup_f32 v50, v49, v51, 1.0
	v_lshlrev_b32_e32 v82, 16, v78
	v_pk_mul_f32 v[82:83], v[50:51], v[82:83] op_sel_hi:[0,1]
	v_lshlrev_b32_e32 v78, 16, v79
	v_and_b32_e32 v79, 0xffff0000, v79
	v_pk_fma_f32 v[44:45], v[28:29], v[82:83], v[44:45]
	s_waitcnt vmcnt(7)
	v_lshlrev_b32_e32 v82, 16, v76
	v_and_b32_e32 v83, 0xffff0000, v76
	v_pk_mul_f32 v[78:79], v[50:51], v[78:79] op_sel_hi:[0,1]
	v_lshlrev_b32_e32 v76, 16, v77
	v_and_b32_e32 v77, 0xffff0000, v77
	v_pk_mul_f32 v[82:83], v[48:49], v[82:83] op_sel_hi:[0,1]
	v_pk_fma_f32 v[46:47], v[30:31], v[78:79], v[46:47]
	v_pk_mul_f32 v[76:77], v[48:49], v[76:77] op_sel_hi:[0,1]
	v_lshl_add_u64 v[80:81], v[62:63], 0, s[0:1]
	v_pk_fma_f32 v[44:45], v[20:21], v[82:83], v[44:45]
	v_pk_fma_f32 v[46:47], v[22:23], v[76:77], v[46:47]
	global_store_dwordx4 v[80:81], v[44:47], off nt
	s_nop 1
	v_lshlrev_b32_e32 v44, 16, v74
	v_and_b32_e32 v45, 0xffff0000, v74
	v_pk_mul_f32 v[44:45], v[50:51], v[44:45] op_sel_hi:[0,1]
	v_pk_fma_f32 v[40:41], v[24:25], v[44:45], v[40:41]
	s_waitcnt vmcnt(7)
	v_lshlrev_b32_e32 v44, 16, v72
	v_and_b32_e32 v45, 0xffff0000, v72
	v_pk_mul_f32 v[44:45], v[48:49], v[44:45] op_sel_hi:[0,1]
	v_pk_fma_f32 v[40:41], v[16:17], v[44:45], v[40:41]
	v_lshlrev_b32_e32 v44, 16, v75
	v_and_b32_e32 v45, 0xffff0000, v75
	v_pk_mul_f32 v[44:45], v[50:51], v[44:45] op_sel_hi:[0,1]
	v_pk_fma_f32 v[42:43], v[26:27], v[44:45], v[42:43]
	v_lshlrev_b32_e32 v44, 16, v73
	v_and_b32_e32 v45, 0xffff0000, v73
	v_pk_mul_f32 v[44:45], v[48:49], v[44:45] op_sel_hi:[0,1]
	v_pk_fma_f32 v[42:43], v[18:19], v[44:45], v[42:43]
	global_store_dwordx4 v[80:81], v[40:43], off offset:1024 nt
	s_nop 1
	v_lshlrev_b32_e32 v40, 16, v70
	v_and_b32_e32 v41, 0xffff0000, v70
	v_pk_mul_f32 v[40:41], v[50:51], v[40:41] op_sel_hi:[0,1]
	v_pk_fma_f32 v[36:37], v[12:13], v[40:41], v[36:37]
	s_waitcnt vmcnt(7)
	v_lshlrev_b32_e32 v40, 16, v68
	v_and_b32_e32 v41, 0xffff0000, v68
	v_pk_mul_f32 v[40:41], v[48:49], v[40:41] op_sel_hi:[0,1]
	v_pk_fma_f32 v[36:37], v[4:5], v[40:41], v[36:37]
	v_lshlrev_b32_e32 v40, 16, v71
	v_and_b32_e32 v41, 0xffff0000, v71
	v_pk_mul_f32 v[40:41], v[50:51], v[40:41] op_sel_hi:[0,1]
	v_pk_fma_f32 v[38:39], v[14:15], v[40:41], v[38:39]
	v_lshlrev_b32_e32 v40, 16, v69
	v_and_b32_e32 v41, 0xffff0000, v69
	v_pk_mul_f32 v[40:41], v[48:49], v[40:41] op_sel_hi:[0,1]
	v_pk_fma_f32 v[38:39], v[6:7], v[40:41], v[38:39]
	global_store_dwordx4 v[80:81], v[36:39], off offset:2048 nt
	s_nop 1
	v_lshlrev_b32_e32 v36, 16, v66
	v_and_b32_e32 v37, 0xffff0000, v66
	v_pk_mul_f32 v[36:37], v[50:51], v[36:37] op_sel_hi:[0,1]
	v_pk_fma_f32 v[32:33], v[8:9], v[36:37], v[32:33]
	s_waitcnt vmcnt(7)
	v_lshlrev_b32_e32 v36, 16, v64
	v_and_b32_e32 v37, 0xffff0000, v64
	v_pk_mul_f32 v[36:37], v[48:49], v[36:37] op_sel_hi:[0,1]
	v_pk_fma_f32 v[32:33], v[0:1], v[36:37], v[32:33]
	v_lshlrev_b32_e32 v36, 16, v67
	v_and_b32_e32 v37, 0xffff0000, v67
	v_pk_mul_f32 v[36:37], v[50:51], v[36:37] op_sel_hi:[0,1]
	v_pk_fma_f32 v[34:35], v[10:11], v[36:37], v[34:35]
	v_lshlrev_b32_e32 v36, 16, v65
	v_and_b32_e32 v37, 0xffff0000, v65
	v_pk_mul_f32 v[36:37], v[48:49], v[36:37] op_sel_hi:[0,1]
	v_pk_fma_f32 v[34:35], v[2:3], v[36:37], v[34:35]
	global_store_dwordx4 v[80:81], v[32:35], off offset:3072 nt
	s_branch .LBB0_1034
